# speedup vs baseline: 1.0765x; 1.0060x over previous
; #define MFMA16(a, b, c) __builtin_amdgcn_mfma_f32_16x16x32_bf16(a, b, c, 0, 0, 0)
; __device__ __forceinline__ void attn_item(KP p, const int h, const int t0, const int lane) {
;     ...
;   for (int s0 = (t0 >> 6) << 6; s0 >= 0; s0 -= 64) {
;     f32x4 st[2][4];
; #pragma unroll
;     for (int kb = 0; kb < 4; ++kb) {
;       st[0][kb] = f32x4{0.f, 0.f, 0.f, 0.f}; st[1][kb] = f32x4{0.f, 0.f, 0.f, 0.f};
;       const int key = s0 + 32 * (kb >> 1) + (fr >> 2) * 8 + (kb & 1) * 4 + (fr & 3);
;       const u16* kp = p->k + (size_t)key * 1024 + h * 128 + g * 8;
; #pragma unroll
;       for (int ks = 0; ks < 4; ++ks) {
;         bf16x8 kf = *(const bf16x8*)(kp + ks * 32);
;         st[0][kb] = MFMA16(kf, qf[0][ks], st[0][kb]);
;         st[1][kb] = MFMA16(kf, qf[1][ks], st[1][kb]);
;       }
;     }
;     ...
;         for (int j = 0; j < 8; ++j) {
;           const float z = st[nb][h2 * 2 + (j >> 2)][j & 3];
;           const int key = s0 + 32 * h2 + g * 8 + j;
;           const float sp = fmaxf(z, 0.f) + __logf(1.f + __expf(-fabsf(z)));
.LBB0_439:
	v_add_u32_e32 v192, s56, v153
	v_lshlrev_b64 v[96:97], 11, v[192:193]
	v_lshl_add_u64 v[96:97], v[130:131], 0, v[96:97]
	global_load_dwordx4 v[228:231], v[96:97], off
	global_load_dwordx4 v[232:235], v[96:97], off offset:64
	global_load_dwordx4 v[236:239], v[96:97], off offset:128
	global_load_dwordx4 v[240:243], v[96:97], off offset:192
	v_add_u32_e32 v98, 4, v192
	v_mov_b32_e32 v99, v193
	v_lshlrev_b64 v[98:99], 11, v[98:99]
	v_lshl_add_u64 v[98:99], v[130:131], 0, v[98:99]
	global_load_dwordx4 v[244:247], v[98:99], off
	global_load_dwordx4 v[248:251], v[98:99], off offset:64
	global_load_dwordx4 v[160:163], v[98:99], off offset:128
	global_load_dwordx4 v[164:167], v[98:99], off offset:192
	v_add_u32_e32 v100, 32, v192
	v_mov_b32_e32 v101, v193
	v_lshlrev_b64 v[100:101], 11, v[100:101]
	v_lshl_add_u64 v[100:101], v[130:131], 0, v[100:101]
	global_load_dwordx4 v[168:171], v[100:101], off
	global_load_dwordx4 v[172:175], v[100:101], off offset:64
	global_load_dwordx4 v[176:179], v[100:101], off offset:128
	global_load_dwordx4 v[180:183], v[100:101], off offset:192
	v_add_u32_e32 v102, 36, v192
	v_mov_b32_e32 v103, v193
	v_lshlrev_b64 v[102:103], 11, v[102:103]
	v_lshl_add_u64 v[102:103], v[130:131], 0, v[102:103]
	global_load_dwordx4 v[184:187], v[102:103], off
	global_load_dwordx4 v[188:191], v[102:103], off offset:64
	global_load_dwordx4 v[154:157], v[102:103], off offset:128
	global_load_dwordx4 v[204:207], v[102:103], off offset:192
	s_waitcnt vmcnt(15)
	v_mfma_f32_16x16x32_bf16 v[112:115], v[228:231], v[0:3], 0
	v_mfma_f32_16x16x32_bf16 v[104:107], v[228:231], v[16:19], 0
	s_waitcnt vmcnt(14)
	v_mfma_f32_16x16x32_bf16 v[112:115], v[232:235], v[4:7], v[112:115]
	v_mfma_f32_16x16x32_bf16 v[104:107], v[232:235], v[20:23], v[104:107]
	s_waitcnt vmcnt(13)
	v_mfma_f32_16x16x32_bf16 v[112:115], v[236:239], v[8:11], v[112:115]
	v_mfma_f32_16x16x32_bf16 v[104:107], v[236:239], v[24:27], v[104:107]
	s_waitcnt vmcnt(12)
	v_mfma_f32_16x16x32_bf16 v[112:115], v[240:243], v[12:15], v[112:115]
	v_mfma_f32_16x16x32_bf16 v[104:107], v[240:243], v[28:31], v[104:107]
	s_waitcnt vmcnt(11)
	v_mfma_f32_16x16x32_bf16 v[96:99], v[244:247], v[0:3], 0
	v_mfma_f32_16x16x32_bf16 v[100:103], v[244:247], v[16:19], 0
	s_waitcnt vmcnt(10)
	v_mfma_f32_16x16x32_bf16 v[96:99], v[248:251], v[4:7], v[96:99]
	v_mfma_f32_16x16x32_bf16 v[100:103], v[248:251], v[20:23], v[100:103]
	s_waitcnt vmcnt(9)
	v_mfma_f32_16x16x32_bf16 v[96:99], v[160:163], v[8:11], v[96:99]
	v_mfma_f32_16x16x32_bf16 v[100:103], v[160:163], v[24:27], v[100:103]
	s_waitcnt vmcnt(8)
	v_mfma_f32_16x16x32_bf16 v[96:99], v[164:167], v[12:15], v[96:99]
	v_mfma_f32_16x16x32_bf16 v[100:103], v[164:167], v[28:31], v[100:103]
	s_waitcnt vmcnt(7)
	v_mfma_f32_16x16x32_bf16 v[120:123], v[168:171], v[0:3], 0
	v_mfma_f32_16x16x32_bf16 v[116:119], v[168:171], v[16:19], 0
	s_waitcnt vmcnt(6)
	v_mfma_f32_16x16x32_bf16 v[120:123], v[172:175], v[4:7], v[120:123]
	v_mfma_f32_16x16x32_bf16 v[116:119], v[172:175], v[20:23], v[116:119]
	s_waitcnt vmcnt(5)
	v_mfma_f32_16x16x32_bf16 v[120:123], v[176:179], v[8:11], v[120:123]
	v_mfma_f32_16x16x32_bf16 v[116:119], v[176:179], v[24:27], v[116:119]
	s_waitcnt vmcnt(4)
	v_mfma_f32_16x16x32_bf16 v[120:123], v[180:183], v[12:15], v[120:123]
	v_mfma_f32_16x16x32_bf16 v[116:119], v[180:183], v[28:31], v[116:119]
	s_waitcnt vmcnt(3)
	v_mfma_f32_16x16x32_bf16 v[124:127], v[184:187], v[0:3], 0
	v_mfma_f32_16x16x32_bf16 v[108:111], v[184:187], v[16:19], 0
	s_waitcnt vmcnt(2)
	v_mfma_f32_16x16x32_bf16 v[124:127], v[188:191], v[4:7], v[124:127]
	v_mfma_f32_16x16x32_bf16 v[108:111], v[188:191], v[20:23], v[108:111]
	s_waitcnt vmcnt(1)
	v_mfma_f32_16x16x32_bf16 v[124:127], v[154:157], v[8:11], v[124:127]
	v_mfma_f32_16x16x32_bf16 v[108:111], v[154:157], v[24:27], v[108:111]
	s_waitcnt vmcnt(0)
	v_mfma_f32_16x16x32_bf16 v[124:127], v[204:207], v[12:15], v[124:127]
	v_mfma_f32_16x16x32_bf16 v[108:111], v[204:207], v[28:31], v[108:111]
	s_nop 7
	v_mul_f32_e64 v168, |v103|, s89
	v_mul_f32_e64 v176, |v116|, s89
	v_exp_f32_e32 v168, v168
	v_exp_f32_e32 v176, v176
	v_add_f32_e32 v168, 1.0, v168
	v_add_f32_e32 v176, 1.0, v176
	v_mul_f32_e64 v156, |v112|, s89
	v_exp_f32_e32 v156, v156
	v_max_f32_e32 v155, v112, v112
	v_max_f32_e32 v155, 0, v155
	v_add_u32_e32 v154, s56, v128
	v_add_f32_e32 v156, 1.0, v156
	v_cmp_gt_f32_e32 vcc, s77, v156
	v_add_u32_e32 v166, 32, v154
	v_add_u32_e32 v170, 33, v154
	v_cndmask_b32_e64 v157, 0, 32, vcc
	v_ldexp_f32 v156, v156, v157
	v_log_f32_e32 v156, v156
	v_add_u32_e32 v206, 4, v154
	v_add_u32_e32 v207, 5, v154
	v_add_u32_e32 v208, 6, v154
	v_mul_f32_e32 v157, 0x3f317217, v156
	v_fma_f32 v157, v156, s93, -v157
	v_fmac_f32_e32 v157, 0x3377d1cf, v156
	v_fmac_f32_e32 v157, 0x3f317217, v156
	v_cmp_lt_f32_e64 s[10:11], |v156|, s94
	v_add_u32_e32 v217, 7, v154
	v_add_u32_e32 v172, 35, v154
	v_cndmask_b32_e64 v156, v156, v157, s[10:11]
	v_cndmask_b32_e32 v157, 0, v215, vcc
	v_sub_f32_e32 v156, v156, v157
	v_mul_f32_e64 v157, |v113|, s89
	v_exp_f32_e32 v157, v157
	v_add_f32_e32 v155, v155, v156
	v_cmp_lt_u32_e32 vcc, v154, v129
	v_sub_f32_e32 v112, v112, v155
	v_add_f32_e32 v157, 1.0, v157
	v_cndmask_b32_e32 v192, v216, v112, vcc
	v_sub_f32_e32 v112, 0, v155
	v_cndmask_b32_e32 v112, 0, v112, vcc
	v_cmp_gt_f32_e32 vcc, s77, v157
	v_max_f32_e32 v155, v113, v113
	v_max_f32_e32 v155, 0, v155
	v_cndmask_b32_e64 v158, 0, 32, vcc
	v_ldexp_f32 v157, v157, v158
	v_log_f32_e32 v157, v157
	v_add_u32_e32 v156, 1, v154
	v_add_u32_e32 v218, 36, v154
	v_add_u32_e32 v219, 37, v154
	v_mul_f32_e32 v158, 0x3f317217, v157
	v_fma_f32 v158, v157, s93, -v158
	v_fmac_f32_e32 v158, 0x3377d1cf, v157
; __device__ __forceinline__ void attn_item(KP p, const int h, const int t0, const int lane) {
;     ...
; #pragma unroll
;       for (int h2 = 0; h2 < 2; ++h2) {
;         T[h2] = 0.f;
; #pragma unroll
;         for (int j = 0; j < 8; ++j) {
;           const float z = st[nb][h2 * 2 + (j >> 2)][j & 3];
;           const int key = s0 + 32 * h2 + g * 8 + j;
;           const float sp = fmaxf(z, 0.f) + __logf(1.f + __expf(-fabsf(z)));
;           const bool valid = key < t;
;           lm[h2][j] = valid ? -sp : 0.f;
;           lsg[h2][j] = valid ? (z - sp) : -1e30f;
;           T[h2] += lm[h2][j];
;         }
;       }
	v_fmac_f32_e32 v158, 0x3f317217, v157
	v_cmp_lt_f32_e64 s[10:11], |v157|, s94
	v_add_u32_e32 v220, 38, v154
	v_add_u32_e32 v221, 39, v154
	v_cndmask_b32_e64 v157, v157, v158, s[10:11]
	v_cndmask_b32_e32 v158, 0, v215, vcc
	v_sub_f32_e32 v157, v157, v158
	v_add_f32_e32 v155, v155, v157
	v_mul_f32_e64 v157, |v114|, s89
	v_exp_f32_e32 v157, v157
	v_cmp_lt_u32_e32 vcc, v156, v129
	v_sub_f32_e32 v113, v113, v155
	v_cmp_lt_u32_e64 s[30:31], v172, v152
	v_add_f32_e32 v157, 1.0, v157
	v_cndmask_b32_e64 v201, 0, -v155, vcc
	v_cndmask_b32_e32 v202, v216, v113, vcc
	v_cmp_gt_f32_e32 vcc, s77, v157
	v_max_f32_e32 v113, v114, v114
	v_add_f32_e32 v155, v201, v112
	v_cndmask_b32_e64 v158, 0, 32, vcc
	v_ldexp_f32 v157, v157, v158
	v_log_f32_e32 v157, v157
	v_add_u32_e32 v112, 2, v154
	v_max_f32_e32 v113, 0, v113
	v_mul_f32_e64 v180, |v111|, s89
	v_mul_f32_e32 v158, 0x3f317217, v157
	v_fma_f32 v158, v157, s93, -v158
	v_fmac_f32_e32 v158, 0x3377d1cf, v157
	v_fmac_f32_e32 v158, 0x3f317217, v157
	v_cmp_lt_f32_e64 s[10:11], |v157|, s94
	v_exp_f32_e32 v180, v180
	v_cmp_lt_u32_e64 s[36:37], v206, v129
	v_cndmask_b32_e64 v157, v157, v158, s[10:11]
	v_cndmask_b32_e32 v158, 0, v215, vcc
	v_sub_f32_e32 v157, v157, v158
	v_add_f32_e32 v157, v113, v157
	v_cmp_lt_u32_e32 vcc, v112, v129
	v_sub_f32_e32 v114, v114, v157
	v_add_u32_e32 v158, 3, v154
	v_cndmask_b32_e64 v113, 0, -v157, vcc
	v_max_f32_e32 v157, v115, v115
	v_max_f32_e32 v189, 0, v157
	v_mul_f32_e64 v157, |v115|, s89
	v_exp_f32_e32 v157, v157
	v_cndmask_b32_e32 v114, v216, v114, vcc
	v_add_f32_e32 v180, 1.0, v180
	v_cmp_lt_u32_e64 s[38:39], v207, v129
	v_add_f32_e32 v157, 1.0, v157
	v_cmp_gt_f32_e32 vcc, s77, v157
	v_cmp_lt_u32_e64 s[40:41], v208, v129
	v_cmp_lt_u32_e64 s[42:43], v217, v129
	v_cndmask_b32_e64 v159, 0, 32, vcc
	v_ldexp_f32 v157, v157, v159
	v_log_f32_e32 v157, v157
	v_cmp_lt_u32_e64 s[44:45], v218, v129
	v_cmp_lt_u32_e64 s[46:47], v219, v129
	v_cmp_lt_u32_e64 s[18:19], v208, v152
	v_mul_f32_e32 v159, 0x3f317217, v157
	v_fma_f32 v159, v157, s93, -v159
	v_fmac_f32_e32 v159, 0x3377d1cf, v157
	v_fmac_f32_e32 v159, 0x3f317217, v157
	v_cmp_lt_f32_e64 s[10:11], |v157|, s94
	v_cmp_lt_u32_e64 s[48:49], v220, v129
	v_cmp_lt_u32_e64 s[20:21], v217, v152
	v_cndmask_b32_e64 v157, v157, v159, s[10:11]
	v_cndmask_b32_e32 v159, 0, v215, vcc
	v_sub_f32_e32 v199, v157, v159
	v_max_f32_e32 v157, v96, v96
	v_max_f32_e32 v185, 0, v157
	v_mul_f32_e64 v157, |v96|, s89
	v_exp_f32_e32 v157, v157
	v_cmp_lt_u32_e32 vcc, v158, v129
	v_cmp_lt_u32_e64 s[50:51], v221, v129
	v_cmp_lt_u32_e64 s[22:23], v218, v152
	v_add_f32_e32 v157, 1.0, v157
	v_cmp_gt_f32_e64 s[10:11], s77, v157
	v_cmp_lt_u32_e64 s[24:25], v219, v152
	v_cmp_lt_u32_e64 s[26:27], v220, v152
	v_cndmask_b32_e64 v159, 0, 32, s[10:11]
	v_ldexp_f32 v157, v157, v159
	v_log_f32_e32 v157, v157
	v_cmp_lt_u32_e64 s[28:29], v221, v152
	v_mul_f32_e32 v159, 0x3f317217, v157
	v_fma_f32 v159, v157, s93, -v159
	v_fmac_f32_e32 v159, 0x3377d1cf, v157
	v_fmac_f32_e32 v159, 0x3f317217, v157
	v_cmp_lt_f32_e64 s[12:13], |v157|, s94
	s_nop 1
	v_cndmask_b32_e64 v157, v157, v159, s[12:13]
	v_cndmask_b32_e64 v159, 0, v215, s[10:11]
	v_sub_f32_e32 v195, v157, v159
	v_mul_f32_e64 v159, |v97|, s89
	v_exp_f32_e32 v159, v159
	v_max_f32_e32 v157, v97, v97
	v_max_f32_e32 v157, 0, v157
	v_add_f32_e32 v159, 1.0, v159
	v_cmp_gt_f32_e64 s[10:11], s77, v159
	s_nop 1
	v_cndmask_b32_e64 v160, 0, 32, s[10:11]
	v_ldexp_f32 v159, v159, v160
	v_log_f32_e32 v159, v159
	s_nop 0
	v_mul_f32_e32 v160, 0x3f317217, v159
	v_fma_f32 v160, v159, s93, -v160
	v_fmac_f32_e32 v160, 0x3377d1cf, v159
	v_fmac_f32_e32 v160, 0x3f317217, v159
	v_cmp_lt_f32_e64 s[12:13], |v159|, s94
	s_nop 1
	v_cndmask_b32_e64 v159, v159, v160, s[12:13]
	v_cndmask_b32_e64 v160, 0, v215, s[10:11]
	v_sub_f32_e32 v161, v159, v160
	v_mul_f32_e64 v160, |v98|, s89
	v_exp_f32_e32 v160, v160
	v_max_f32_e32 v159, v98, v98
	v_max_f32_e32 v159, 0, v159
	v_add_f32_e32 v160, 1.0, v160
	v_cmp_gt_f32_e64 s[10:11], s77, v160
	s_nop 1
	v_cndmask_b32_e64 v162, 0, 32, s[10:11]
	v_ldexp_f32 v160, v160, v162
	v_log_f32_e32 v160, v160
	s_nop 0
	v_mul_f32_e32 v162, 0x3f317217, v160
	v_fma_f32 v162, v160, s93, -v162
	v_fmac_f32_e32 v162, 0x3377d1cf, v160
	v_fmac_f32_e32 v162, 0x3f317217, v160
	v_cmp_lt_f32_e64 s[12:13], |v160|, s94
	s_nop 1
	v_cndmask_b32_e64 v160, v160, v162, s[12:13]
	v_cndmask_b32_e64 v162, 0, v215, s[10:11]
	v_sub_f32_e32 v165, v160, v162
	v_max_f32_e32 v160, v99, v99
	v_max_f32_e32 v163, 0, v160
	v_mul_f32_e64 v160, |v99|, s89
	v_exp_f32_e32 v160, v160
	s_nop 0
	v_add_f32_e32 v160, 1.0, v160
	v_cmp_gt_f32_e64 s[10:11], s77, v160
	s_nop 1
	v_cndmask_b32_e64 v162, 0, 32, s[10:11]
	v_ldexp_f32 v160, v160, v162
	v_log_f32_e32 v160, v160
	s_nop 0
	v_mul_f32_e32 v162, 0x3f317217, v160
	v_fma_f32 v162, v160, s93, -v162
	v_fmac_f32_e32 v162, 0x3377d1cf, v160
	v_fmac_f32_e32 v162, 0x3f317217, v160
	v_cmp_lt_f32_e64 s[12:13], |v160|, s94
	s_nop 1
	v_cndmask_b32_e64 v160, v160, v162, s[12:13]
	v_cndmask_b32_e64 v162, 0, v215, s[10:11]
	v_sub_f32_e32 v169, v160, v162
	v_mul_f32_e64 v162, |v120|, s89
	v_exp_f32_e32 v162, v162
	v_max_f32_e32 v160, v120, v120
	v_max_f32_e32 v160, 0, v160
	v_add_f32_e32 v162, 1.0, v162
	v_cmp_gt_f32_e64 s[10:11], s77, v162
	s_nop 1
	v_cndmask_b32_e64 v164, 0, 32, s[10:11]
	v_ldexp_f32 v162, v162, v164
	v_log_f32_e32 v162, v162
	s_nop 0
	v_mul_f32_e32 v164, 0x3f317217, v162
	v_fma_f32 v164, v162, s93, -v164
	v_fmac_f32_e32 v164, 0x3377d1cf, v162
	v_fmac_f32_e32 v164, 0x3f317217, v162
	v_cmp_lt_f32_e64 s[12:13], |v162|, s94
	s_nop 1
	v_cndmask_b32_e64 v162, v162, v164, s[12:13]
	v_cndmask_b32_e64 v164, 0, v215, s[10:11]
; __device__ __forceinline__ void attn_item(KP p, const int h, const int t0, const int lane) {
;     ...
; #pragma unroll
;       for (int h2 = 0; h2 < 2; ++h2) {
;         T[h2] = 0.f;
; #pragma unroll
;         for (int j = 0; j < 8; ++j) {
;           const float z = st[nb][h2 * 2 + (j >> 2)][j & 3];
;           const int key = s0 + 32 * h2 + g * 8 + j;
;           const float sp = fmaxf(z, 0.f) + __logf(1.f + __expf(-fabsf(z)));
;           const bool valid = key < t;
;           lm[h2][j] = valid ? -sp : 0.f;
;           lsg[h2][j] = valid ? (z - sp) : -1e30f;
;           T[h2] += lm[h2][j];
;         }
;       }
	v_sub_f32_e32 v162, v162, v164
	v_add_f32_e32 v160, v160, v162
	v_mul_f32_e64 v162, |v121|, s89
	v_exp_f32_e32 v162, v162
	v_cmp_lt_u32_e64 s[10:11], v166, v129
	v_sub_f32_e32 v120, v120, v160
	v_add_f32_e32 v162, 1.0, v162
	v_cndmask_b32_e64 v203, v216, v120, s[10:11]
	v_sub_f32_e32 v120, 0, v160
	v_cndmask_b32_e64 v120, 0, v120, s[10:11]
	v_cmp_gt_f32_e64 s[10:11], s77, v162
	v_max_f32_e32 v160, v121, v121
	v_max_f32_e32 v160, 0, v160
	v_cndmask_b32_e64 v164, 0, 32, s[10:11]
	v_ldexp_f32 v162, v162, v164
	v_log_f32_e32 v162, v162
	s_nop 0
	v_mul_f32_e32 v164, 0x3f317217, v162
	v_fma_f32 v164, v162, s93, -v164
	v_fmac_f32_e32 v164, 0x3377d1cf, v162
	v_fmac_f32_e32 v164, 0x3f317217, v162
	v_cmp_lt_f32_e64 s[12:13], |v162|, s94
	s_nop 1
	v_cndmask_b32_e64 v162, v162, v164, s[12:13]
	v_cndmask_b32_e64 v164, 0, v215, s[10:11]
	v_sub_f32_e32 v162, v162, v164
	v_add_f32_e32 v160, v160, v162
	v_cmp_lt_u32_e64 s[10:11], v170, v129
	v_sub_f32_e32 v121, v121, v160
	s_nop 0
	v_cndmask_b32_e64 v204, 0, -v160, s[10:11]
	v_mul_f32_e64 v160, |v122|, s89
	v_exp_f32_e32 v160, v160
	v_cndmask_b32_e64 v205, v216, v121, s[10:11]
	v_max_f32_e32 v121, v122, v122
	v_add_f32_e32 v167, v204, v120
	v_add_f32_e32 v160, 1.0, v160
	v_cmp_gt_f32_e64 s[10:11], s77, v160
	v_add_u32_e32 v120, 34, v154
	v_max_f32_e32 v121, 0, v121
	v_cndmask_b32_e64 v162, 0, 32, s[10:11]
	v_ldexp_f32 v160, v160, v162
	v_log_f32_e32 v160, v160
	s_nop 0
	v_mul_f32_e32 v162, 0x3f317217, v160
	v_fma_f32 v162, v160, s93, -v162
	v_fmac_f32_e32 v162, 0x3377d1cf, v160
	v_fmac_f32_e32 v162, 0x3f317217, v160
	v_cmp_lt_f32_e64 s[12:13], |v160|, s94
	s_nop 1
	v_cndmask_b32_e64 v160, v160, v162, s[12:13]
	v_cndmask_b32_e64 v162, 0, v215, s[10:11]
	v_sub_f32_e32 v160, v160, v162
	v_add_f32_e32 v160, v121, v160
	v_cmp_lt_u32_e64 s[10:11], v120, v129
	v_sub_f32_e32 v122, v122, v160
	s_nop 0
	v_cndmask_b32_e64 v121, 0, -v160, s[10:11]
	v_max_f32_e32 v160, v123, v123
	v_max_f32_e32 v187, 0, v160
	v_mul_f32_e64 v160, |v123|, s89
	v_exp_f32_e32 v160, v160
	v_cndmask_b32_e64 v122, v216, v122, s[10:11]
	v_add_f32_e32 v160, 1.0, v160
	v_cmp_gt_f32_e64 s[10:11], s77, v160
	s_nop 1
	v_cndmask_b32_e64 v162, 0, 32, s[10:11]
	v_ldexp_f32 v160, v160, v162
	v_log_f32_e32 v160, v160
	s_nop 0
	v_mul_f32_e32 v162, 0x3f317217, v160
	v_fma_f32 v162, v160, s93, -v162
	v_fmac_f32_e32 v162, 0x3377d1cf, v160
	v_fmac_f32_e32 v162, 0x3f317217, v160
	v_cmp_lt_f32_e64 s[12:13], |v160|, s94
	s_nop 1
	v_cndmask_b32_e64 v160, v160, v162, s[12:13]
	v_cndmask_b32_e64 v162, 0, v215, s[10:11]
	v_sub_f32_e32 v197, v160, v162
	v_max_f32_e32 v160, v124, v124
	v_max_f32_e32 v183, 0, v160
	v_mul_f32_e64 v160, |v124|, s89
	v_exp_f32_e32 v160, v160
	v_cmp_lt_u32_e64 s[10:11], v172, v129
	v_mul_f32_e64 v172, |v109|, s89
	v_exp_f32_e32 v172, v172
	v_add_f32_e32 v160, 1.0, v160
	v_cmp_gt_f32_e64 s[12:13], s77, v160
	v_add_f32_e32 v172, 1.0, v172
	s_nop 0
	v_cndmask_b32_e64 v162, 0, 32, s[12:13]
	v_ldexp_f32 v160, v160, v162
	v_log_f32_e32 v160, v160
	s_nop 0
	v_mul_f32_e32 v162, 0x3f317217, v160
	v_fma_f32 v162, v160, s93, -v162
	v_fmac_f32_e32 v162, 0x3377d1cf, v160
	v_fmac_f32_e32 v162, 0x3f317217, v160
	v_cmp_lt_f32_e64 s[14:15], |v160|, s94
	s_nop 1
	v_cndmask_b32_e64 v160, v160, v162, s[14:15]
	v_cndmask_b32_e64 v162, 0, v215, s[12:13]
	v_sub_f32_e32 v191, v160, v162
	v_max_f32_e32 v160, v125, v125
	v_max_f32_e32 v171, 0, v160
	v_mul_f32_e64 v160, |v125|, s89
	v_exp_f32_e32 v160, v160
	s_nop 0
	v_add_f32_e32 v160, 1.0, v160
	v_cmp_gt_f32_e64 s[12:13], s77, v160
	s_nop 1
	v_cndmask_b32_e64 v162, 0, 32, s[12:13]
	v_ldexp_f32 v160, v160, v162
	v_log_f32_e32 v160, v160
	s_nop 0
	v_mul_f32_e32 v162, 0x3f317217, v160
	v_fma_f32 v162, v160, s93, -v162
	v_fmac_f32_e32 v162, 0x3377d1cf, v160
	v_fmac_f32_e32 v162, 0x3f317217, v160
	v_cmp_lt_f32_e64 s[14:15], |v160|, s94
	s_nop 1
	v_cndmask_b32_e64 v160, v160, v162, s[14:15]
	v_cndmask_b32_e64 v162, 0, v215, s[12:13]
	v_sub_f32_e32 v175, v160, v162
	v_max_f32_e32 v160, v126, v126
	v_max_f32_e32 v173, 0, v160
	v_mul_f32_e64 v160, |v126|, s89
	v_exp_f32_e32 v160, v160
	s_nop 0
	v_add_f32_e32 v160, 1.0, v160
	v_cmp_gt_f32_e64 s[12:13], s77, v160
	s_nop 1
	v_cndmask_b32_e64 v162, 0, 32, s[12:13]
	v_ldexp_f32 v160, v160, v162
	v_log_f32_e32 v160, v160
	s_nop 0
	v_mul_f32_e32 v162, 0x3f317217, v160
	v_fma_f32 v162, v160, s93, -v162
	v_fmac_f32_e32 v162, 0x3377d1cf, v160
	v_fmac_f32_e32 v162, 0x3f317217, v160
	v_cmp_lt_f32_e64 s[14:15], |v160|, s94
	s_nop 1
	v_cndmask_b32_e64 v160, v160, v162, s[14:15]
	v_cndmask_b32_e64 v162, 0, v215, s[12:13]
	v_sub_f32_e32 v179, v160, v162
	v_max_f32_e32 v160, v127, v127
	v_max_f32_e32 v177, 0, v160
	v_mul_f32_e64 v160, |v127|, s89
	v_exp_f32_e32 v160, v160
	s_nop 0
	v_add_f32_e32 v160, 1.0, v160
	v_cmp_gt_f32_e64 s[12:13], s77, v160
	s_nop 1
	v_cndmask_b32_e64 v162, 0, 32, s[12:13]
	v_ldexp_f32 v160, v160, v162
	v_log_f32_e32 v160, v160
	s_nop 0
	v_mul_f32_e32 v162, 0x3f317217, v160
	v_fma_f32 v162, v160, s93, -v162
	v_fmac_f32_e32 v162, 0x3377d1cf, v160
	v_fmac_f32_e32 v162, 0x3f317217, v160
	v_cmp_lt_f32_e64 s[14:15], |v160|, s94
	s_nop 1
	v_cndmask_b32_e64 v160, v160, v162, s[14:15]
	v_cndmask_b32_e64 v162, 0, v215, s[12:13]
	v_sub_f32_e32 v181, v160, v162
	v_mul_f32_e64 v162, |v104|, s89
	v_exp_f32_e32 v162, v162
	v_max_f32_e32 v160, v104, v104
	v_max_f32_e32 v160, 0, v160
	v_add_f32_e32 v162, 1.0, v162
	v_cmp_gt_f32_e64 s[12:13], s77, v162
	s_nop 1
	v_cndmask_b32_e64 v164, 0, 32, s[12:13]
	v_ldexp_f32 v162, v162, v164
	v_log_f32_e32 v162, v162
	s_nop 0
	v_mul_f32_e32 v164, 0x3f317217, v162
	v_fma_f32 v164, v162, s93, -v164
	v_fmac_f32_e32 v164, 0x3377d1cf, v162
; __device__ __forceinline__ void attn_item(KP p, const int h, const int t0, const int lane) {
;     ...
; #pragma unroll
;       for (int h2 = 0; h2 < 2; ++h2) {
;         T[h2] = 0.f;
; #pragma unroll
;         for (int j = 0; j < 8; ++j) {
;           const float z = st[nb][h2 * 2 + (j >> 2)][j & 3];
;           const int key = s0 + 32 * h2 + g * 8 + j;
;           const float sp = fmaxf(z, 0.f) + __logf(1.f + __expf(-fabsf(z)));
;           const bool valid = key < t;
;           lm[h2][j] = valid ? -sp : 0.f;
;           lsg[h2][j] = valid ? (z - sp) : -1e30f;
;           T[h2] += lm[h2][j];
;         }
;       }
	v_fmac_f32_e32 v164, 0x3f317217, v162
	v_cmp_lt_f32_e64 s[14:15], |v162|, s94
	s_nop 1
	v_cndmask_b32_e64 v162, v162, v164, s[14:15]
	v_cndmask_b32_e64 v164, 0, v215, s[12:13]
	v_sub_f32_e32 v162, v162, v164
	v_add_f32_e32 v160, v160, v162
	v_cmp_lt_u32_e64 s[12:13], v154, v152
	v_sub_f32_e32 v104, v104, v160
	v_max_f32_e32 v154, v105, v105
	v_cndmask_b32_e64 v209, v216, v104, s[12:13]
	v_sub_f32_e32 v104, 0, v160
	v_mul_f32_e64 v160, |v105|, s89
	v_exp_f32_e32 v160, v160
	v_cndmask_b32_e64 v104, 0, v104, s[12:13]
	v_max_f32_e32 v154, 0, v154
	v_add_f32_e32 v160, 1.0, v160
	v_cmp_gt_f32_e64 s[12:13], s77, v160
	s_nop 1
	v_cndmask_b32_e64 v162, 0, 32, s[12:13]
	v_ldexp_f32 v160, v160, v162
	v_log_f32_e32 v160, v160
	s_nop 0
	v_mul_f32_e32 v162, 0x3f317217, v160
	v_fma_f32 v162, v160, s93, -v162
	v_fmac_f32_e32 v162, 0x3377d1cf, v160
	v_fmac_f32_e32 v162, 0x3f317217, v160
	v_cmp_lt_f32_e64 s[14:15], |v160|, s94
	s_nop 1
	v_cndmask_b32_e64 v160, v160, v162, s[14:15]
	v_cndmask_b32_e64 v162, 0, v215, s[12:13]
	v_sub_f32_e32 v160, v160, v162
	v_add_f32_e32 v154, v154, v160
	v_cmp_lt_u32_e64 s[12:13], v156, v152
	v_sub_f32_e32 v105, v105, v154
	v_mul_f32_e64 v162, |v102|, s89
	v_cndmask_b32_e64 v223, v216, v105, s[12:13]
	v_mul_f32_e64 v105, |v106|, s89
	v_exp_f32_e32 v105, v105
	v_cndmask_b32_e64 v222, 0, -v154, s[12:13]
	v_add_f32_e32 v154, v222, v104
	v_max_f32_e32 v104, v106, v106
	v_add_f32_e32 v105, 1.0, v105
	v_cmp_gt_f32_e64 s[12:13], s77, v105
	v_max_f32_e32 v104, 0, v104
	v_exp_f32_e32 v162, v162
	v_cndmask_b32_e64 v156, 0, 32, s[12:13]
	v_ldexp_f32 v105, v105, v156
	v_log_f32_e32 v105, v105
	v_add_f32_e32 v162, 1.0, v162
	v_mul_f32_e32 v156, 0x3f317217, v105
	v_fma_f32 v156, v105, s93, -v156
	v_fmac_f32_e32 v156, 0x3377d1cf, v105
	v_fmac_f32_e32 v156, 0x3f317217, v105
	v_cmp_lt_f32_e64 s[14:15], |v105|, s94
	s_nop 1
	v_cndmask_b32_e64 v105, v105, v156, s[14:15]
	v_cndmask_b32_e64 v156, 0, v215, s[12:13]
	v_sub_f32_e32 v105, v105, v156
	v_add_f32_e32 v104, v104, v105
	v_cmp_lt_u32_e64 s[12:13], v112, v152
	v_max_f32_e32 v156, v101, v101
	v_max_f32_e32 v156, 0, v156
	v_cndmask_b32_e64 v112, 0, -v104, s[12:13]
	v_sub_f32_e32 v104, v106, v104
	v_cndmask_b32_e64 v224, v216, v104, s[12:13]
	v_max_f32_e32 v104, v107, v107
	v_max_f32_e32 v188, 0, v104
	v_mul_f32_e64 v104, |v107|, s89
	v_exp_f32_e32 v104, v104
	s_nop 0
	v_add_f32_e32 v104, 1.0, v104
	v_cmp_gt_f32_e64 s[12:13], s77, v104
	s_nop 1
	v_cndmask_b32_e64 v105, 0, 32, s[12:13]
	v_ldexp_f32 v104, v104, v105
	v_log_f32_e32 v104, v104
	s_nop 0
	v_mul_f32_e32 v105, 0x3f317217, v104
	v_fma_f32 v105, v104, s93, -v105
	v_fmac_f32_e32 v105, 0x3377d1cf, v104
	v_fmac_f32_e32 v105, 0x3f317217, v104
	v_cmp_lt_f32_e64 s[14:15], |v104|, s94
	s_nop 1
	v_cndmask_b32_e64 v104, v104, v105, s[14:15]
	v_cndmask_b32_e64 v105, 0, v215, s[12:13]
	v_sub_f32_e32 v198, v104, v105
	v_pk_add_f32 v[104:105], v[188:189], v[198:199]
	v_cmp_lt_u32_e64 s[12:13], v158, v152
	v_sub_f32_e32 v106, v115, v105
	v_cndmask_b32_e32 v115, v216, v106, vcc
	v_sub_f32_e32 v106, v107, v104
	v_cndmask_b32_e64 v198, v216, v106, s[12:13]
	v_max_f32_e32 v106, v100, v100
	v_max_f32_e32 v184, 0, v106
	v_mul_f32_e64 v106, |v100|, s89
	v_exp_f32_e32 v106, v106
	v_mul_f32_e64 v158, |v101|, s89
	v_exp_f32_e32 v158, v158
	v_add_f32_e32 v106, 1.0, v106
	v_cmp_gt_f32_e64 s[14:15], s77, v106
	v_add_f32_e32 v158, 1.0, v158
	s_nop 0
	v_cndmask_b32_e64 v107, 0, 32, s[14:15]
	v_ldexp_f32 v106, v106, v107
	v_log_f32_e32 v106, v106
	s_nop 0
	v_mul_f32_e32 v107, 0x3f317217, v106
	v_fma_f32 v107, v106, s93, -v107
	v_fmac_f32_e32 v107, 0x3377d1cf, v106
	v_fmac_f32_e32 v107, 0x3f317217, v106
	v_cmp_lt_f32_e64 s[16:17], |v106|, s94
	s_nop 1
	v_cndmask_b32_e64 v106, v106, v107, s[16:17]
	v_cndmask_b32_e64 v107, 0, v215, s[14:15]
	v_cmp_gt_f32_e64 s[14:15], s77, v158
	v_sub_f32_e32 v194, v106, v107
	v_pk_add_f32 v[106:107], v[184:185], v[194:195]
	v_cndmask_b32_e64 v160, 0, 32, s[14:15]
	v_ldexp_f32 v158, v158, v160
	v_log_f32_e32 v158, v158
	v_sub_f32_e32 v96, v96, v107
	v_sub_f32_e32 v100, v100, v106
	v_mul_f32_e32 v160, 0x3f317217, v158
	v_fma_f32 v160, v158, s93, -v160
	v_fmac_f32_e32 v160, 0x3377d1cf, v158
	v_fmac_f32_e32 v160, 0x3f317217, v158
	v_cmp_lt_f32_e64 s[16:17], |v158|, s94
	s_nop 1
	v_cndmask_b32_e64 v158, v158, v160, s[16:17]
	v_cndmask_b32_e64 v160, 0, v215, s[14:15]
	v_cmp_gt_f32_e64 s[14:15], s77, v162
	v_sub_f32_e32 v160, v158, v160
	v_max_f32_e32 v158, v102, v102
	v_cndmask_b32_e64 v164, 0, 32, s[14:15]
	v_ldexp_f32 v162, v162, v164
	v_log_f32_e32 v162, v162
	v_max_f32_e32 v158, 0, v158
	v_pk_add_f32 v[156:157], v[156:157], v[160:161]
	v_mul_f32_e32 v164, 0x3f317217, v162
	v_fma_f32 v164, v162, s93, -v164
	v_fmac_f32_e32 v164, 0x3377d1cf, v162
	v_fmac_f32_e32 v164, 0x3f317217, v162
	v_cmp_lt_f32_e64 s[16:17], |v162|, s94
	s_nop 1
	v_cndmask_b32_e64 v162, v162, v164, s[16:17]
	v_cndmask_b32_e64 v164, 0, v215, s[14:15]
	v_cmp_gt_f32_e64 s[14:15], s77, v168
	v_sub_f32_e32 v164, v162, v164
	v_max_f32_e32 v162, v103, v103
	v_cndmask_b32_e64 v174, 0, 32, s[14:15]
	v_ldexp_f32 v168, v168, v174
	v_log_f32_e32 v168, v168
	v_max_f32_e32 v162, 0, v162
	v_pk_add_f32 v[158:159], v[158:159], v[164:165]
	v_mul_f32_e32 v174, 0x3f317217, v168
	v_fma_f32 v174, v168, s93, -v174
	v_fmac_f32_e32 v174, 0x3377d1cf, v168
	v_fmac_f32_e32 v174, 0x3f317217, v168
	v_cmp_lt_f32_e64 s[16:17], |v168|, s94
	s_nop 1
	v_cndmask_b32_e64 v168, v168, v174, s[16:17]
	v_cndmask_b32_e64 v174, 0, v215, s[14:15]
	v_cmp_gt_f32_e64 s[14:15], s77, v176
	v_sub_f32_e32 v168, v168, v174
	v_max_f32_e32 v174, v116, v116
	v_cndmask_b32_e64 v178, 0, 32, s[14:15]
	v_ldexp_f32 v176, v176, v178
; __device__ __forceinline__ void attn_item(KP p, const int h, const int t0, const int lane) {
;     ...
; #pragma unroll
;       for (int h2 = 0; h2 < 2; ++h2) {
;         T[h2] = 0.f;
; #pragma unroll
;         for (int j = 0; j < 8; ++j) {
;           const float z = st[nb][h2 * 2 + (j >> 2)][j & 3];
;           const int key = s0 + 32 * h2 + g * 8 + j;
;           const float sp = fmaxf(z, 0.f) + __logf(1.f + __expf(-fabsf(z)));
;           const bool valid = key < t;
;           lm[h2][j] = valid ? -sp : 0.f;
;           lsg[h2][j] = valid ? (z - sp) : -1e30f;
;           T[h2] += lm[h2][j];
;         }
;       }
	v_log_f32_e32 v176, v176
	v_max_f32_e32 v174, 0, v174
	v_pk_add_f32 v[160:161], v[162:163], v[168:169]
	v_cndmask_b32_e64 v169, 0, -v157, s[38:39]
	v_mul_f32_e32 v178, 0x3f317217, v176
	v_fma_f32 v178, v176, s93, -v178
	v_fmac_f32_e32 v178, 0x3377d1cf, v176
	v_fmac_f32_e32 v178, 0x3f317217, v176
	v_cmp_lt_f32_e64 s[16:17], |v176|, s94
	s_nop 1
	v_cndmask_b32_e64 v176, v176, v178, s[16:17]
	v_cndmask_b32_e64 v178, 0, v215, s[14:15]
	v_sub_f32_e32 v176, v176, v178
	v_add_f32_e32 v174, v174, v176
	v_cmp_lt_u32_e64 s[14:15], v166, v152
	v_sub_f32_e32 v116, v116, v174
	v_max_f32_e32 v166, v117, v117
	v_cndmask_b32_e64 v199, v216, v116, s[14:15]
	v_sub_f32_e32 v116, 0, v174
	v_mul_f32_e64 v174, |v117|, s89
	v_exp_f32_e32 v174, v174
	v_cndmask_b32_e64 v116, 0, v116, s[14:15]
	v_max_f32_e32 v166, 0, v166
	v_add_f32_e32 v174, 1.0, v174
	v_cmp_gt_f32_e64 s[14:15], s77, v174
	s_nop 1
	v_cndmask_b32_e64 v176, 0, 32, s[14:15]
	v_ldexp_f32 v174, v174, v176
	v_log_f32_e32 v174, v174
	s_nop 0
	v_mul_f32_e32 v176, 0x3f317217, v174
	v_fma_f32 v176, v174, s93, -v176
	v_fmac_f32_e32 v176, 0x3377d1cf, v174
	v_fmac_f32_e32 v176, 0x3f317217, v174
	v_cmp_lt_f32_e64 s[16:17], |v174|, s94
	s_nop 1
	v_cndmask_b32_e64 v174, v174, v176, s[16:17]
	v_cndmask_b32_e64 v176, 0, v215, s[14:15]
	v_sub_f32_e32 v174, v174, v176
	v_add_f32_e32 v166, v166, v174
	v_cmp_lt_u32_e64 s[14:15], v170, v152
	v_sub_f32_e32 v117, v117, v166
	v_mul_f32_e64 v176, |v110|, s89
	v_cndmask_b32_e64 v226, v216, v117, s[14:15]
	v_mul_f32_e64 v117, |v118|, s89
	v_exp_f32_e32 v117, v117
	v_cndmask_b32_e64 v225, 0, -v166, s[14:15]
	v_add_f32_e32 v166, v225, v116
	v_max_f32_e32 v116, v118, v118
	v_add_f32_e32 v117, 1.0, v117
	v_cmp_gt_f32_e64 s[14:15], s77, v117
	v_max_f32_e32 v116, 0, v116
	v_exp_f32_e32 v176, v176
	v_cndmask_b32_e64 v170, 0, 32, s[14:15]
	v_ldexp_f32 v117, v117, v170
	v_log_f32_e32 v117, v117
	v_add_f32_e32 v176, 1.0, v176
	v_mul_f32_e32 v170, 0x3f317217, v117
	v_fma_f32 v170, v117, s93, -v170
	v_fmac_f32_e32 v170, 0x3377d1cf, v117
	v_fmac_f32_e32 v170, 0x3f317217, v117
	v_cmp_lt_f32_e64 s[16:17], |v117|, s94
	s_nop 1
	v_cndmask_b32_e64 v117, v117, v170, s[16:17]
	v_cndmask_b32_e64 v170, 0, v215, s[14:15]
	v_sub_f32_e32 v117, v117, v170
	v_add_f32_e32 v116, v116, v117
	v_cmp_lt_u32_e64 s[14:15], v120, v152
	v_max_f32_e32 v170, v109, v109
	v_max_f32_e32 v170, 0, v170
	v_cndmask_b32_e64 v120, 0, -v116, s[14:15]
	v_sub_f32_e32 v116, v118, v116
	v_cndmask_b32_e64 v227, v216, v116, s[14:15]
	v_max_f32_e32 v116, v119, v119
	v_max_f32_e32 v186, 0, v116
	v_mul_f32_e64 v116, |v119|, s89
	v_exp_f32_e32 v116, v116
	s_nop 0
	v_add_f32_e32 v116, 1.0, v116
	v_cmp_gt_f32_e64 s[14:15], s77, v116
	s_nop 1
	v_cndmask_b32_e64 v117, 0, 32, s[14:15]
	v_ldexp_f32 v116, v116, v117
	v_log_f32_e32 v116, v116
	s_nop 0
	v_mul_f32_e32 v117, 0x3f317217, v116
	v_fma_f32 v117, v116, s93, -v117
	v_fmac_f32_e32 v117, 0x3377d1cf, v116
	v_fmac_f32_e32 v117, 0x3f317217, v116
	v_cmp_lt_f32_e64 s[16:17], |v116|, s94
	s_nop 1
	v_cndmask_b32_e64 v116, v116, v117, s[16:17]
	v_cndmask_b32_e64 v117, 0, v215, s[14:15]
	v_sub_f32_e32 v196, v116, v117
	v_pk_add_f32 v[116:117], v[186:187], v[196:197]
	v_cndmask_b32_e64 v197, v216, v96, s[36:37]
	v_sub_f32_e32 v118, v123, v117
	v_cndmask_b32_e64 v123, v216, v118, s[10:11]
	v_sub_f32_e32 v118, v119, v116
	v_cndmask_b32_e64 v196, v216, v118, s[30:31]
	v_max_f32_e32 v118, v108, v108
	v_max_f32_e32 v182, 0, v118
	v_mul_f32_e64 v118, |v108|, s89
	v_exp_f32_e32 v118, v118
	v_sub_f32_e32 v96, v97, v157
	v_cndmask_b32_e64 v117, 0, -v117, s[10:11]
	v_cndmask_b32_e64 v116, 0, -v116, s[30:31]
	v_add_f32_e32 v118, 1.0, v118
	v_cmp_gt_f32_e64 s[14:15], s77, v118
	s_nop 1
	v_cndmask_b32_e64 v119, 0, 32, s[14:15]
	v_ldexp_f32 v118, v118, v119
	v_log_f32_e32 v118, v118
	s_nop 0
	v_mul_f32_e32 v119, 0x3f317217, v118
	v_fma_f32 v119, v118, s93, -v119
	v_fmac_f32_e32 v119, 0x3377d1cf, v118
	v_fmac_f32_e32 v119, 0x3f317217, v118
	v_cmp_lt_f32_e64 s[16:17], |v118|, s94
	s_nop 1
	v_cndmask_b32_e64 v118, v118, v119, s[16:17]
	v_cndmask_b32_e64 v119, 0, v215, s[14:15]
	v_cmp_gt_f32_e64 s[14:15], s77, v172
	v_sub_f32_e32 v190, v118, v119
	v_pk_add_f32 v[118:119], v[182:183], v[190:191]
	v_cndmask_b32_e64 v174, 0, 32, s[14:15]
	v_ldexp_f32 v172, v172, v174
	v_log_f32_e32 v172, v172
	v_sub_f32_e32 v124, v124, v119
	v_sub_f32_e32 v108, v108, v118
	v_cndmask_b32_e64 v119, 0, -v119, s[44:45]
	v_mul_f32_e32 v174, 0x3f317217, v172
	v_fma_f32 v174, v172, s93, -v174
	v_fmac_f32_e32 v174, 0x3377d1cf, v172
	v_fmac_f32_e32 v174, 0x3f317217, v172
	v_cmp_lt_f32_e64 s[16:17], |v172|, s94
	v_cndmask_b32_e64 v118, 0, -v118, s[22:23]
	s_nop 0
	v_cndmask_b32_e64 v172, v172, v174, s[16:17]
	v_cndmask_b32_e64 v174, 0, v215, s[14:15]
	v_cmp_gt_f32_e64 s[14:15], s77, v176
	v_sub_f32_e32 v174, v172, v174
	v_max_f32_e32 v172, v110, v110
	v_cndmask_b32_e64 v178, 0, 32, s[14:15]
	v_ldexp_f32 v176, v176, v178
	v_log_f32_e32 v176, v176
	v_max_f32_e32 v172, 0, v172
	v_pk_add_f32 v[162:163], v[170:171], v[174:175]
	v_cndmask_b32_e64 v171, 0, -v159, s[40:41]
	v_mul_f32_e32 v178, 0x3f317217, v176
	v_fma_f32 v178, v176, s93, -v178
	v_fmac_f32_e32 v178, 0x3377d1cf, v176
	v_fmac_f32_e32 v178, 0x3f317217, v176
	v_cmp_lt_f32_e64 s[16:17], |v176|, s94
	v_cndmask_b32_e64 v170, 0, -v158, s[18:19]
	s_nop 0
	v_cndmask_b32_e64 v176, v176, v178, s[16:17]
	v_cndmask_b32_e64 v178, 0, v215, s[14:15]
	v_cmp_gt_f32_e64 s[14:15], s77, v180
	v_sub_f32_e32 v178, v176, v178
	v_max_f32_e32 v176, v111, v111
	v_cndmask_b32_e64 v182, 0, 32, s[14:15]
	v_ldexp_f32 v180, v180, v182
	v_log_f32_e32 v180, v180
	v_max_f32_e32 v176, 0, v176
	v_mul_f32_e32 v182, 0x3f317217, v180
; __device__ __forceinline__ void attn_item(KP p, const int h, const int t0, const int lane) {
;     ...
;       float suf[2], tot[2];
; #pragma unroll
;       for (int h2 = 0; h2 < 2; ++h2) {
;         const float a = T[h2];
;         const float b = swz_xor<16>(a);
;         const float c = xor32(a, lane);
;         const float d = xor32(b, lane);
;         tot[h2] = a + b + c + d;
;         suf[h2] = (((g ^ 1) > g) ? b : 0.f) + (((g ^ 2) > g) ? c : 0.f) + (((g ^ 3) > g) ? d : 0.f);
;       }
; #pragma unroll
;       for (int h2 = 0; h2 < 2; ++h2) {
;         float run = R[nb] + suf[h2] + (h2 == 0 ? tot[1] : 0.f);
;         float a[8];
; #pragma unroll
;         for (int j = 7; j >= 0; --j) {
;           a[j] = __expf(lsg[h2][j] + run);
;           run += lm[h2][j];
;         }
;         bf16x8 pk;
; #pragma unroll
;         for (int j = 0; j < 8; ++j) pk[j] = (short)f2bf(a[j]);
;         pf[nb][h2] = pk;
;       }
	v_fma_f32 v182, v180, s93, -v182
	v_fmac_f32_e32 v182, 0x3377d1cf, v180
	v_fmac_f32_e32 v182, 0x3f317217, v180
	v_cmp_lt_f32_e64 s[16:17], |v180|, s94
	s_nop 1
	v_cndmask_b32_e64 v180, v180, v182, s[16:17]
	v_cndmask_b32_e64 v182, 0, v215, s[14:15]
	v_cmp_lt_u32_e64 s[14:15], v206, v152
	v_cndmask_b32_e64 v206, v216, v96, s[38:39]
	v_sub_f32_e32 v96, v98, v159
	v_cndmask_b32_e64 v98, v216, v96, s[40:41]
	v_sub_f32_e32 v96, v99, v161
	v_sub_f32_e32 v180, v180, v182
	v_cmp_lt_u32_e64 s[16:17], v207, v152
	v_cndmask_b32_e64 v99, v216, v96, s[42:43]
	v_cndmask_b32_e64 v207, v216, v124, s[44:45]
	v_sub_f32_e32 v96, v125, v163
	v_pk_add_f32 v[124:125], v[172:173], v[178:179]
	v_cndmask_b32_e64 v208, v216, v96, s[46:47]
	v_sub_f32_e32 v96, v126, v125
	v_pk_add_f32 v[164:165], v[176:177], v[180:181]
	v_cndmask_b32_e64 v217, v216, v96, s[48:49]
	v_sub_f32_e32 v96, v127, v165
	v_cndmask_b32_e64 v218, v216, v96, s[50:51]
	v_pk_add_f32 v[96:97], v[112:113], v[154:155]
	v_cndmask_b32_e64 v127, 0, -v105, vcc
	v_cndmask_b32_e64 v126, 0, -v104, s[12:13]
	v_pk_add_f32 v[96:97], v[126:127], v[96:97]
	v_cndmask_b32_e64 v155, 0, -v107, s[36:37]
	v_cndmask_b32_e64 v154, 0, -v106, s[14:15]
	v_pk_add_f32 v[96:97], v[96:97], v[154:155]
	v_cndmask_b32_e64 v168, 0, -v156, s[16:17]
	v_pk_add_f32 v[96:97], v[168:169], v[96:97]
	v_cndmask_b32_e64 v173, 0, -v161, s[42:43]
	v_pk_add_f32 v[96:97], v[170:171], v[96:97]
	v_cndmask_b32_e64 v172, 0, -v160, s[20:21]
	v_pk_add_f32 v[174:175], v[172:173], v[96:97]
	ds_swizzle_b32 v177, v175 offset:swizzle(SWAP,16)
	ds_bpermute_b32 v179, v200, v175
	v_cndmask_b32_e64 v183, 0, -v125, s[48:49]
	v_cndmask_b32_e64 v182, 0, -v124, s[26:27]
	v_cndmask_b32_e64 v185, 0, -v165, s[50:51]
	s_waitcnt lgkmcnt(1)
	ds_bpermute_b32 v181, v200, v177
	v_cndmask_b32_e64 v96, 0, v177, s[4:5]
	s_waitcnt lgkmcnt(1)
	v_cndmask_b32_e64 v97, 0, v179, s[6:7]
	v_add_f32_e32 v96, v96, v97
	v_cndmask_b32_e64 v184, 0, -v164, s[28:29]
	s_waitcnt lgkmcnt(0)
	v_cndmask_b32_e64 v97, 0, v181, s[8:9]
	v_add_f32_e32 v104, v96, v97
	v_pk_add_f32 v[96:97], v[120:121], v[166:167]
	v_cndmask_b32_e64 v167, 0, -v163, s[46:47]
	v_pk_add_f32 v[96:97], v[116:117], v[96:97]
	v_cndmask_b32_e64 v166, 0, -v162, s[24:25]
	v_pk_add_f32 v[96:97], v[96:97], v[118:119]
	v_add_f32_e32 v104, v151, v104
	v_pk_add_f32 v[96:97], v[166:167], v[96:97]
	ds_swizzle_b32 v176, v174 offset:swizzle(SWAP,16)
	v_pk_add_f32 v[96:97], v[182:183], v[96:97]
	ds_bpermute_b32 v178, v200, v174
	v_pk_add_f32 v[96:97], v[184:185], v[96:97]
	ds_swizzle_b32 v187, v97 offset:swizzle(SWAP,16)
	ds_swizzle_b32 v186, v96 offset:swizzle(SWAP,16)
	ds_bpermute_b32 v189, v200, v97
	ds_bpermute_b32 v188, v200, v96
	s_waitcnt lgkmcnt(5)
	ds_bpermute_b32 v180, v200, v176
	s_waitcnt lgkmcnt(4)
	ds_bpermute_b32 v191, v200, v187
	s_waitcnt lgkmcnt(4)
	ds_bpermute_b32 v190, v200, v186
	v_pk_add_f32 v[96:97], v[96:97], v[186:187]
	v_cndmask_b32_e64 v105, 0, v187, s[4:5]
	s_waitcnt lgkmcnt(3)
	v_pk_add_f32 v[96:97], v[96:97], v[188:189]
	v_cndmask_b32_e64 v106, 0, v189, s[6:7]
	s_waitcnt lgkmcnt(0)
	v_pk_add_f32 v[194:195], v[96:97], v[190:191]
	v_add_f32_e32 v105, v105, v106
	v_add_f32_e32 v96, v104, v195
	v_add_f32_e32 v97, v99, v96
	v_add_f32_e32 v96, v173, v96
	v_add_f32_e32 v98, v98, v96
	v_add_f32_e32 v96, v171, v96
	v_add_f32_e32 v99, v206, v96
	v_add_f32_e32 v96, v169, v96
	v_cndmask_b32_e64 v106, 0, v191, s[8:9]
	v_add_f32_e32 v104, v197, v96
	v_add_f32_e32 v96, v155, v96
	v_add_f32_e32 v125, v105, v106
	v_add_f32_e32 v105, v115, v96
	v_add_f32_e32 v96, v127, v96
	v_add_f32_e32 v106, v114, v96
	v_mul_f32_e32 v106, 0x3fb8aa3b, v106
	v_add_f32_e32 v96, v113, v96
	v_exp_f32_e32 v114, v106
	v_add_f32_e32 v106, v202, v96
	v_add_f32_e32 v96, v201, v96
	v_add_f32_e32 v96, v192, v96
	v_mul_f32_e32 v99, 0x3fb8aa3b, v99
	v_mul_f32_e32 v104, 0x3fb8aa3b, v104
	v_mul_f32_e32 v106, 0x3fb8aa3b, v106
	v_mul_f32_e32 v96, 0x3fb8aa3b, v96
	v_exp_f32_e32 v99, v99
	v_exp_f32_e32 v104, v104
	v_exp_f32_e32 v113, v106
	v_exp_f32_e32 v96, v96
	v_mul_f32_e32 v97, 0x3fb8aa3b, v97
	v_mul_f32_e32 v98, 0x3fb8aa3b, v98
	v_exp_f32_e32 v97, v97
	v_exp_f32_e32 v98, v98
	v_cvt_pk_bf16_f32 v106, v104, v99
	v_cvt_pk_bf16_f32 v104, v96, v113
	v_add_f32_e32 v96, v151, v125
	v_add_f32_e32 v96, 0, v96
	v_cvt_pk_bf16_f32 v107, v98, v97
	v_add_f32_e32 v97, v218, v96
	v_add_f32_e32 v96, v185, v96
	v_mul_f32_e32 v105, 0x3fb8aa3b, v105
	v_add_f32_e32 v98, v217, v96
	v_add_f32_e32 v96, v183, v96
	v_exp_f32_e32 v105, v105
	v_add_f32_e32 v99, v208, v96
	v_mul_f32_e32 v99, 0x3fb8aa3b, v99
	v_add_f32_e32 v96, v167, v96
	v_exp_f32_e32 v113, v99
	v_add_f32_e32 v99, v207, v96
	v_mul_f32_e32 v99, 0x3fb8aa3b, v99
	v_add_f32_e32 v96, v119, v96
	v_cvt_pk_bf16_f32 v105, v114, v105
	v_exp_f32_e32 v114, v99
	v_add_f32_e32 v99, v123, v96
	v_mul_f32_e32 v99, 0x3fb8aa3b, v99
	v_add_f32_e32 v96, v117, v96
	v_mul_f32_e32 v97, 0x3fb8aa3b, v97
	v_mul_f32_e32 v98, 0x3fb8aa3b, v98
	v_exp_f32_e32 v115, v99
	v_add_f32_e32 v99, v122, v96
	v_exp_f32_e32 v97, v97
	v_exp_f32_e32 v98, v98
	v_mul_f32_e32 v99, 0x3fb8aa3b, v99
	v_exp_f32_e32 v117, v99
	v_add_f32_e32 v96, v121, v96
	v_add_f32_e32 v99, v205, v96
	v_mul_f32_e32 v99, 0x3fb8aa3b, v99
	v_exp_f32_e32 v119, v99
	v_cvt_pk_bf16_f32 v99, v98, v97
	v_cvt_pk_bf16_f32 v98, v114, v113
	v_cndmask_b32_e64 v113, v216, v100, s[14:15]
	v_sub_f32_e32 v100, v101, v156
	v_cvt_pk_bf16_f32 v97, v117, v115
	v_cndmask_b32_e64 v117, v216, v100, s[16:17]
	v_sub_f32_e32 v100, v102, v158
	v_cndmask_b32_e64 v102, v216, v100, s[18:19]
	v_sub_f32_e32 v100, v103, v160
	v_cndmask_b32_e64 v103, v216, v100, s[20:21]
	v_sub_f32_e32 v100, v109, v162
; __device__ __forceinline__ int perm_row(int b, int i) { return (b >> 1) * 32 + (i >> 2) * 8 + (b & 1) * 4 + (i & 3); }
; #define MFMA16(a, b, c) __builtin_amdgcn_mfma_f32_16x16x32_bf16(a, b, c, 0, 0, 0)
; __device__ __forceinline__ void attn_item(KP p, const int h, const int t0, const int lane) {
;     ...
;       for (int h2 = 0; h2 < 2; ++h2) {
;         float run = R[nb] + suf[h2] + (h2 == 0 ? tot[1] : 0.f);
;         float a[8];
; #pragma unroll
;         for (int j = 7; j >= 0; --j) {
;           a[j] = __expf(lsg[h2][j] + run);
;           run += lm[h2][j];
;         }
;         bf16x8 pk;
; #pragma unroll
;         for (int j = 0; j < 8; ++j) pk[j] = (short)f2bf(a[j]);
;         pf[nb][h2] = pk;
;       }
;       R[nb] += tot[0] + tot[1];
;     }
; #pragma unroll
;     for (int h2 = 0; h2 < 2; ++h2)
; #pragma unroll
;       for (int mb = 0; mb < 8; ++mb) {
;         const bf16x8 vf = *(const bf16x8*)(p->vT + (size_t)(h * 128 + perm_row(mb, fr)) * S_ + s0 + 32 * h2 + g * 8);
;         o[0][mb] = MFMA16(vf, pf[0][h2], o[0][mb]);
;         o[1][mb] = MFMA16(vf, pf[1][h2], o[1][mb]);
	v_cndmask_b32_e64 v121, v216, v100, s[24:25]
	v_sub_f32_e32 v100, v110, v124
	v_cndmask_b32_e64 v122, v216, v100, s[26:27]
	v_sub_f32_e32 v100, v111, v164
	v_add_f32_e32 v96, v204, v96
	v_cndmask_b32_e64 v123, v216, v100, s[28:29]
	v_pk_add_f32 v[100:101], v[174:175], v[176:177]
	v_add_f32_e32 v96, v203, v96
	v_pk_add_f32 v[100:101], v[100:101], v[178:179]
	v_mul_f32_e32 v96, 0x3fb8aa3b, v96
	v_pk_add_f32 v[114:115], v[100:101], v[180:181]
	v_cndmask_b32_e64 v100, 0, v176, s[4:5]
	v_cndmask_b32_e64 v101, 0, v178, s[6:7]
	v_exp_f32_e32 v96, v96
	v_add_f32_e32 v100, v100, v101
	v_cndmask_b32_e64 v101, 0, v180, s[8:9]
	v_add_f32_e32 v100, v100, v101
	v_add_f32_e32 v100, v150, v100
	v_add_f32_e32 v100, v100, v194
	v_cvt_pk_bf16_f32 v96, v96, v119
	v_cndmask_b32_e64 v119, v216, v108, s[22:23]
	v_cndmask_b32_e64 v101, 0, v186, s[4:5]
	v_cndmask_b32_e64 v108, 0, v188, s[6:7]
	v_add_f32_e32 v103, v103, v100
	v_add_f32_e32 v100, v172, v100
	v_add_f32_e32 v101, v101, v108
	v_cndmask_b32_e64 v108, 0, v190, s[8:9]
	v_add_f32_e32 v102, v102, v100
	v_add_f32_e32 v100, v170, v100
	v_add_f32_e32 v101, v101, v108
	v_add_f32_e32 v108, v117, v100
	v_add_f32_e32 v100, v168, v100
	v_add_f32_e32 v109, v113, v100
	v_add_f32_e32 v100, v154, v100
	v_add_f32_e32 v110, v198, v100
	v_mul_f32_e32 v110, 0x3fb8aa3b, v110
	v_add_f32_e32 v100, v126, v100
	v_exp_f32_e32 v113, v110
	v_add_f32_e32 v110, v224, v100
	v_mul_f32_e32 v110, 0x3fb8aa3b, v110
	v_add_f32_e32 v100, v112, v100
	v_exp_f32_e32 v117, v110
	v_add_f32_e32 v110, v223, v100
	v_add_f32_e32 v100, v222, v100
	v_add_f32_e32 v100, v209, v100
	v_mul_f32_e32 v108, 0x3fb8aa3b, v108
	v_mul_f32_e32 v109, 0x3fb8aa3b, v109
	v_mul_f32_e32 v110, 0x3fb8aa3b, v110
	v_mul_f32_e32 v100, 0x3fb8aa3b, v100
	v_exp_f32_e32 v108, v108
	v_exp_f32_e32 v109, v109
	v_exp_f32_e32 v112, v110
	v_exp_f32_e32 v100, v100
	v_mul_f32_e32 v103, 0x3fb8aa3b, v103
	v_mul_f32_e32 v102, 0x3fb8aa3b, v102
	v_exp_f32_e32 v103, v103
	v_exp_f32_e32 v102, v102
	v_cvt_pk_bf16_f32 v110, v109, v108
	v_cvt_pk_bf16_f32 v108, v100, v112
	v_add_f32_e32 v100, v150, v101
	v_add_f32_e32 v100, 0, v100
	v_add_f32_e32 v101, v123, v100
	v_add_f32_e32 v100, v184, v100
	v_cvt_pk_bf16_f32 v111, v102, v103
	v_add_f32_e32 v102, v122, v100
	v_add_f32_e32 v100, v182, v100
	v_add_f32_e32 v103, v121, v100
	v_mul_f32_e32 v103, 0x3fb8aa3b, v103
	v_add_f32_e32 v100, v166, v100
	v_exp_f32_e32 v112, v103
	v_add_f32_e32 v103, v119, v100
	v_mul_f32_e32 v103, 0x3fb8aa3b, v103
	v_add_f32_e32 v100, v118, v100
	v_cvt_pk_bf16_f32 v109, v117, v113
	v_exp_f32_e32 v113, v103
	v_add_f32_e32 v103, v196, v100
	v_mul_f32_e32 v101, 0x3fb8aa3b, v101
	v_mul_f32_e32 v102, 0x3fb8aa3b, v102
	v_mul_f32_e32 v103, 0x3fb8aa3b, v103
	v_add_f32_e32 v100, v116, v100
	v_exp_f32_e32 v101, v101
	v_exp_f32_e32 v102, v102
	v_exp_f32_e32 v117, v103
	v_add_f32_e32 v103, v227, v100
	v_mul_f32_e32 v103, 0x3fb8aa3b, v103
	v_add_f32_e32 v100, v120, v100
	v_exp_f32_e32 v116, v103
	v_add_f32_e32 v103, v226, v100
	v_mul_f32_e32 v103, 0x3fb8aa3b, v103
	v_lshl_add_u64 v[158:159], s[56:57], 1, v[132:133]
	v_exp_f32_e32 v118, v103
	v_cvt_pk_bf16_f32 v103, v102, v101
	v_cvt_pk_bf16_f32 v102, v113, v112
	v_pk_add_f32 v[112:113], v[114:115], v[194:195]
	v_lshl_add_u64 v[126:127], v[158:159], 0, v[134:135]
	v_pk_add_f32 v[150:151], v[150:151], v[112:113]
	global_load_dwordx4 v[228:231], v[126:127], off
	v_lshl_add_u64 v[124:125], v[158:159], 0, v[136:137]
	global_load_dwordx4 v[232:235], v[124:125], off
	v_lshl_add_u64 v[122:123], v[158:159], 0, v[138:139]
	global_load_dwordx4 v[236:239], v[122:123], off
	v_lshl_add_u64 v[120:121], v[158:159], 0, v[140:141]
	global_load_dwordx4 v[240:243], v[120:121], off
	v_lshl_add_u64 v[114:115], v[158:159], 0, v[146:147]
	global_load_dwordx4 v[244:247], v[114:115], off
	v_lshl_add_u64 v[112:113], v[158:159], 0, v[148:149]
	global_load_dwordx4 v[248:251], v[112:113], off
	v_add_f32_e32 v100, v225, v100
	v_add_f32_e32 v100, v199, v100
	v_mul_f32_e32 v100, 0x3fb8aa3b, v100
	v_exp_f32_e32 v100, v100
	v_cvt_pk_bf16_f32 v101, v116, v117
	v_lshl_add_u64 v[116:117], v[158:159], 0, v[144:145]
	v_cvt_pk_bf16_f32 v100, v100, v118
	v_lshl_add_u64 v[118:119], v[158:159], 0, v[142:143]
	v_cmp_gt_f32_e32 vcc, s95, v151
	v_cmp_gt_f32_e64 s[10:11], s95, v150
	s_and_b64 s[10:11], vcc, s[10:11]
	s_waitcnt vmcnt(5)
	v_mfma_f32_16x16x32_bf16 v[56:59], v[228:231], v[104:107], v[56:59]
	v_mfma_f32_16x16x32_bf16 v[40:43], v[228:231], v[108:111], v[40:43]
	global_load_dwordx4 v[228:231], v[118:119], off
	s_waitcnt vmcnt(5)
	v_mfma_f32_16x16x32_bf16 v[64:67], v[232:235], v[104:107], v[64:67]
	v_mfma_f32_16x16x32_bf16 v[44:47], v[232:235], v[108:111], v[44:47]
	global_load_dwordx4 v[232:235], v[116:117], off
	s_waitcnt vmcnt(5)
; __device__ __forceinline__ int perm_row(int b, int i) { return (b >> 1) * 32 + (i >> 2) * 8 + (b & 1) * 4 + (i & 3); }
; #define MFMA16(a, b, c) __builtin_amdgcn_mfma_f32_16x16x32_bf16(a, b, c, 0, 0, 0)
; __device__ __forceinline__ void attn_item(KP p, const int h, const int t0, const int lane) {
;     ...
; #pragma unroll
;     for (int h2 = 0; h2 < 2; ++h2)
; #pragma unroll
;       for (int mb = 0; mb < 8; ++mb) {
;         const bf16x8 vf = *(const bf16x8*)(p->vT + (size_t)(h * 128 + perm_row(mb, fr)) * S_ + s0 + 32 * h2 + g * 8);
;         o[0][mb] = MFMA16(vf, pf[0][h2], o[0][mb]);
;         o[1][mb] = MFMA16(vf, pf[1][h2], o[1][mb]);
;       }
;     const bool done = (R[0] < -ATT_THR) && (R[1] < -ATT_THR);
;     if (__all(done)) break;
;   }
; #pragma unroll
;   for (int nb = 0; nb < 2; ++nb)
; #pragma unroll
;     for (int k2 = 0; k2 < 4; ++k2) {
;       uint4 ov;
;       ov.x = pack2(o[nb][2 * k2][0], o[nb][2 * k2][1]);         ov.y = pack2(o[nb][2 * k2][2], o[nb][2 * k2][3]);
;       ov.z = pack2(o[nb][2 * k2 + 1][0], o[nb][2 * k2 + 1][1]); ov.w = pack2(o[nb][2 * k2 + 1][2], o[nb][2 * k2 + 1][3]);
;       *(uint4*)(p->ycat + (size_t)(t0 + nb * 16 + fr) * D_ + h * 128 + k2 * 32 + g * 8) = ov;
;     }
	v_mfma_f32_16x16x32_bf16 v[68:71], v[236:239], v[104:107], v[68:71]
	v_mfma_f32_16x16x32_bf16 v[48:51], v[236:239], v[108:111], v[48:51]
	global_load_dwordx4 v[236:239], v[126:127], off offset:64
	s_waitcnt vmcnt(5)
	v_mfma_f32_16x16x32_bf16 v[80:83], v[240:243], v[104:107], v[80:83]
	v_mfma_f32_16x16x32_bf16 v[52:55], v[240:243], v[108:111], v[52:55]
	global_load_dwordx4 v[240:243], v[124:125], off offset:64
	s_waitcnt vmcnt(5)
	v_mfma_f32_16x16x32_bf16 v[88:91], v[244:247], v[104:107], v[88:91]
	v_mfma_f32_16x16x32_bf16 v[84:87], v[244:247], v[108:111], v[84:87]
	global_load_dwordx4 v[244:247], v[122:123], off offset:64
	s_waitcnt vmcnt(5)
	v_mfma_f32_16x16x32_bf16 v[32:35], v[248:251], v[104:107], v[32:35]
	v_mfma_f32_16x16x32_bf16 v[36:39], v[248:251], v[108:111], v[36:39]
	global_load_dwordx4 v[248:251], v[120:121], off offset:64
	s_waitcnt vmcnt(5)
	v_mfma_f32_16x16x32_bf16 v[76:79], v[228:231], v[104:107], v[76:79]
	v_mfma_f32_16x16x32_bf16 v[60:63], v[228:231], v[108:111], v[60:63]
	global_load_dwordx4 v[228:231], v[114:115], off offset:64
	s_waitcnt vmcnt(5)
	v_mfma_f32_16x16x32_bf16 v[92:95], v[232:235], v[104:107], v[92:95]
	v_mfma_f32_16x16x32_bf16 v[72:75], v[232:235], v[108:111], v[72:75]
	global_load_dwordx4 v[232:235], v[112:113], off offset:64
	s_waitcnt vmcnt(5)
	v_mfma_f32_16x16x32_bf16 v[56:59], v[236:239], v[96:99], v[56:59]
	v_mfma_f32_16x16x32_bf16 v[40:43], v[236:239], v[100:103], v[40:43]
	global_load_dwordx4 v[236:239], v[118:119], off offset:64
	s_waitcnt vmcnt(5)
	v_mfma_f32_16x16x32_bf16 v[64:67], v[240:243], v[96:99], v[64:67]
	v_mfma_f32_16x16x32_bf16 v[44:47], v[240:243], v[100:103], v[44:47]
	global_load_dwordx4 v[240:243], v[116:117], off offset:64
	s_waitcnt vmcnt(5)
	v_mfma_f32_16x16x32_bf16 v[68:71], v[244:247], v[96:99], v[68:71]
	v_mfma_f32_16x16x32_bf16 v[48:51], v[244:247], v[100:103], v[48:51]
	s_waitcnt vmcnt(4)
	v_mfma_f32_16x16x32_bf16 v[80:83], v[248:251], v[96:99], v[80:83]
	v_mfma_f32_16x16x32_bf16 v[52:55], v[248:251], v[100:103], v[52:55]
	s_waitcnt vmcnt(3)
	v_mfma_f32_16x16x32_bf16 v[88:91], v[228:231], v[96:99], v[88:91]
	v_mfma_f32_16x16x32_bf16 v[84:87], v[228:231], v[100:103], v[84:87]
	s_waitcnt vmcnt(2)
	v_mfma_f32_16x16x32_bf16 v[32:35], v[232:235], v[96:99], v[32:35]
	v_mfma_f32_16x16x32_bf16 v[36:39], v[232:235], v[100:103], v[36:39]
	s_waitcnt vmcnt(1)
	v_mfma_f32_16x16x32_bf16 v[76:79], v[236:239], v[96:99], v[76:79]
	v_mfma_f32_16x16x32_bf16 v[60:63], v[236:239], v[100:103], v[60:63]
	s_waitcnt vmcnt(0)
	v_mfma_f32_16x16x32_bf16 v[92:95], v[240:243], v[96:99], v[92:95]
	v_mfma_f32_16x16x32_bf16 v[72:75], v[240:243], v[100:103], v[72:75]
	v_cndmask_b32_e64 v96, 0, 1, s[10:11]
	v_cmp_ne_u32_e32 vcc, 0, v96
	s_cmp_lg_u64 vcc, exec
	s_cselect_b64 s[10:11], -1, 0
	s_sub_i32 s14, s56, 64
	s_cmp_lg_u32 s56, 0
	s_cselect_b64 s[12:13], -1, 0
	s_and_b64 s[10:11], s[12:13], s[10:11]
	s_and_b64 vcc, exec, s[10:11]
	s_mov_b32 s56, s14
	s_cbranch_vccnz .LBB0_439
	s_load_dwordx2 s[4:5], s[0:1], 0xe0
	v_lshlrev_b32_e32 v192, 1, v128
	v_cvt_pk_bf16_f32 v3, v66, v67
	v_cvt_pk_bf16_f32 v2, v64, v65
	s_waitcnt lgkmcnt(0)
	s_add_u32 s4, s4, s80
	s_addc_u32 s5, s5, s81
	v_lshl_add_u64 v[0:1], s[4:5], 0, v[192:193]
	v_lshlrev_b32_e32 v192, 12, v129
	v_lshl_add_u64 v[4:5], v[0:1], 0, v[192:193]
	v_cvt_pk_bf16_f32 v1, v58, v59
	v_cvt_pk_bf16_f32 v0, v56, v57
	global_store_dwordx4 v[4:5], v[0:3], off
	s_mov_b32 s4, 0x10000
	s_add_i32 s73, s73, s66
	v_cvt_pk_bf16_f32 v3, v82, v83
	v_cvt_pk_bf16_f32 v2, v80, v81
	v_cvt_pk_bf16_f32 v1, v70, v71
	v_cvt_pk_bf16_f32 v0, v68, v69
	global_store_dwordx4 v[4:5], v[0:3], off offset:64
	s_cmpk_gt_i32 s73, 0xfff
	s_nop 0
	v_cvt_pk_bf16_f32 v3, v94, v95
	v_cvt_pk_bf16_f32 v2, v92, v93
	v_cvt_pk_bf16_f32 v1, v78, v79
	v_cvt_pk_bf16_f32 v0, v76, v77
	global_store_dwordx4 v[4:5], v[0:3], off offset:128
	s_nop 1
	v_cvt_pk_bf16_f32 v3, v34, v35
	v_cvt_pk_bf16_f32 v2, v32, v33
	v_cvt_pk_bf16_f32 v1, v90, v91
	v_cvt_pk_bf16_f32 v0, v88, v89
	global_store_dwordx4 v[4:5], v[0:3], off offset:192
	v_add_co_u32_e32 v4, vcc, s4, v4
	s_nop 0
	v_cvt_pk_bf16_f32 v3, v46, v47
	v_cvt_pk_bf16_f32 v2, v44, v45
	v_cvt_pk_bf16_f32 v1, v42, v43
	v_cvt_pk_bf16_f32 v0, v40, v41
	v_addc_co_u32_e32 v5, vcc, 0, v5, vcc
	global_store_dwordx4 v[4:5], v[0:3], off
	s_nop 1
	v_cvt_pk_bf16_f32 v3, v54, v55
	v_cvt_pk_bf16_f32 v2, v52, v53
	v_cvt_pk_bf16_f32 v1, v50, v51
	v_cvt_pk_bf16_f32 v0, v48, v49
	global_store_dwordx4 v[4:5], v[0:3], off offset:64
	s_nop 1
	v_cvt_pk_bf16_f32 v3, v74, v75
	v_cvt_pk_bf16_f32 v2, v72, v73
	v_cvt_pk_bf16_f32 v1, v62, v63
	v_cvt_pk_bf16_f32 v0, v60, v61
	global_store_dwordx4 v[4:5], v[0:3], off offset:128
	s_nop 1
	v_cvt_pk_bf16_f32 v3, v38, v39
	v_cvt_pk_bf16_f32 v2, v36, v37
	v_cvt_pk_bf16_f32 v1, v86, v87
	v_cvt_pk_bf16_f32 v0, v84, v85
	global_store_dwordx4 v[4:5], v[0:3], off offset:192
	s_cbranch_scc0 .LBB0_438
